# +E9 final_norm: 7 weight loads issued up front, 8 output stores back to back; +E10 prologue X conversion: 8 row-chunk loads issued together
# speedup vs baseline: 1.0181x; 1.0007x over previous
; __device__ __forceinline__ size_t sfrag(int r, int k) { return ((size_t)(((k >> 5) * 8 + (r >> 4)) * 64 + ((k >> 3) & 3) * 16 + (r & 15))) * 8 + (k & 7); }
; __device__ __forceinline__ void prologue_phase(CArgs* a, LAS unsigned char* lds, int wg, int G) {
;     ...
;     for (int m = gw; m < MT; m += NGW) {
;         const float* src = m < MP ? a->in[0] + (size_t)m * D : a->in[1] + (size_t)(m - MP) * D;
;         const f32x4* xr = (const f32x4*)src + lane; unsigned long long* bo = (unsigned long long*)(XB + (size_t)m * D) + lane;
;         float s = 0.f;
; #pragma unroll
;         for (int j = 0; j < 8; ++j) { const f32x4 v = xr[64 * j]; if (m < MP) bo[64 * j] = pack4_act<0>(v); else *(unsigned long long*)(XB + (size_t)MP * D + sfrag(m - MP, 4 * (lane + 64 * j))) = pack4_act<0>(v); s += (v.x * v.x + v.y * v.y) + (v.z * v.z + v.w * v.w); }
.LBB0_86:
	s_or_b64 exec, exec, s[20:21]
	s_waitcnt lgkmcnt(0)
	v_lshl_add_u64 v[30:31], v[2:3], 0, v[44:45]
	global_load_dwordx4 v[2:5], v[30:31], off
	s_mov_b32 s100, 0x1000
	s_mov_b32 s101, 0
	v_lshl_add_u64 v[240:241], v[30:31], 0, s[100:101]
	global_load_dwordx4 v[212:215], v[30:31], off offset:1024
	global_load_dwordx4 v[216:219], v[30:31], off offset:2048
	global_load_dwordx4 v[220:223], v[30:31], off offset:3072
	global_load_dwordx4 v[224:227], v[240:241], off
	global_load_dwordx4 v[228:231], v[240:241], off offset:1024
	global_load_dwordx4 v[232:235], v[240:241], off offset:2048
	global_load_dwordx4 v[236:239], v[240:241], off offset:3072
	v_lshrrev_b32_e32 v6, 4, v72
	v_and_or_b32 v8, v40, 15, v52
	v_add_u32_e32 v9, v6, v1
	v_lshl_or_b32 v72, v9, 6, v8
	s_waitcnt vmcnt(0)
	v_cvt_pk_bf16_f32 v6, v2, v3
	v_cvt_pk_bf16_f32 v7, v4, v5
	s_and_saveexec_b64 s[20:21], s[10:11]
	s_xor_b64 s[20:21], exec, s[20:21]
	s_cbranch_execz .LBB0_88
	v_lshl_add_u64 v[8:9], v[72:73], 4, v[36:37]
	global_store_dwordx2 v[8:9], v[6:7], off

; __device__ __forceinline__ size_t sfrag(int r, int k) { return ((size_t)(((k >> 5) * 8 + (r >> 4)) * 64 + ((k >> 3) & 3) * 16 + (r & 15))) * 8 + (k & 7); }
; __device__ __forceinline__ void prologue_phase(CArgs* a, LAS unsigned char* lds, int wg, int G) {
;     ...
; #pragma unroll
;         for (int j = 0; j < 8; ++j) { const f32x4 v = xr[64 * j]; if (m < MP) bo[64 * j] = pack4_act<0>(v); else *(unsigned long long*)(XB + (size_t)MP * D + sfrag(m - MP, 4 * (lane + 64 * j))) = pack4_act<0>(v); s += (v.x * v.x + v.y * v.y) + (v.z * v.z + v.w * v.w); }
.LBB0_90:
	s_or_b64 exec, exec, s[20:21]
	v_cvt_pk_bf16_f32 v10, v212, v213
	v_cvt_pk_bf16_f32 v11, v214, v215
	s_and_saveexec_b64 s[20:21], s[10:11]
	s_xor_b64 s[20:21], exec, s[20:21]
	s_cbranch_execz .LBB0_92
	v_add_u32_e32 v12, 0x1000, v72
	v_mov_b32_e32 v13, v73
	v_lshl_add_u64 v[12:13], v[12:13], 4, v[36:37]
	global_store_dwordx2 v[12:13], v[10:11], off

; __device__ __forceinline__ size_t sfrag(int r, int k) { return ((size_t)(((k >> 5) * 8 + (r >> 4)) * 64 + ((k >> 3) & 3) * 16 + (r & 15))) * 8 + (k & 7); }
; __device__ __forceinline__ void prologue_phase(CArgs* a, LAS unsigned char* lds, int wg, int G) {
;     ...
; #pragma unroll
;         for (int j = 0; j < 8; ++j) { const f32x4 v = xr[64 * j]; if (m < MP) bo[64 * j] = pack4_act<0>(v); else *(unsigned long long*)(XB + (size_t)MP * D + sfrag(m - MP, 4 * (lane + 64 * j))) = pack4_act<0>(v); s += (v.x * v.x + v.y * v.y) + (v.z * v.z + v.w * v.w); }
.LBB0_94:
	s_or_b64 exec, exec, s[20:21]
	v_cvt_pk_bf16_f32 v14, v216, v217
	v_cvt_pk_bf16_f32 v15, v218, v219
	s_and_saveexec_b64 s[20:21], s[10:11]
	s_xor_b64 s[20:21], exec, s[20:21]
	s_cbranch_execz .LBB0_96
	v_add_u32_e32 v16, 0x2000, v72
	v_mov_b32_e32 v17, v73
	v_lshl_add_u64 v[16:17], v[16:17], 4, v[36:37]
	global_store_dwordx2 v[16:17], v[14:15], off

; __device__ __forceinline__ size_t sfrag(int r, int k) { return ((size_t)(((k >> 5) * 8 + (r >> 4)) * 64 + ((k >> 3) & 3) * 16 + (r & 15))) * 8 + (k & 7); }
; __device__ __forceinline__ void prologue_phase(CArgs* a, LAS unsigned char* lds, int wg, int G) {
;     ...
; #pragma unroll
;         for (int j = 0; j < 8; ++j) { const f32x4 v = xr[64 * j]; if (m < MP) bo[64 * j] = pack4_act<0>(v); else *(unsigned long long*)(XB + (size_t)MP * D + sfrag(m - MP, 4 * (lane + 64 * j))) = pack4_act<0>(v); s += (v.x * v.x + v.y * v.y) + (v.z * v.z + v.w * v.w); }
.LBB0_98:
	s_or_b64 exec, exec, s[20:21]
	v_cvt_pk_bf16_f32 v18, v220, v221
	v_cvt_pk_bf16_f32 v19, v222, v223
	s_and_saveexec_b64 s[20:21], s[10:11]
	s_xor_b64 s[20:21], exec, s[20:21]
	s_cbranch_execz .LBB0_100
	v_add_u32_e32 v20, 0x3000, v72
	v_mov_b32_e32 v21, v73
	v_lshl_add_u64 v[20:21], v[20:21], 4, v[36:37]
	global_store_dwordx2 v[20:21], v[18:19], off

; __device__ __forceinline__ size_t sfrag(int r, int k) { return ((size_t)(((k >> 5) * 8 + (r >> 4)) * 64 + ((k >> 3) & 3) * 16 + (r & 15))) * 8 + (k & 7); }
; __device__ __forceinline__ void prologue_phase(CArgs* a, LAS unsigned char* lds, int wg, int G) {
;     ...
; #pragma unroll
;         for (int j = 0; j < 8; ++j) { const f32x4 v = xr[64 * j]; if (m < MP) bo[64 * j] = pack4_act<0>(v); else *(unsigned long long*)(XB + (size_t)MP * D + sfrag(m - MP, 4 * (lane + 64 * j))) = pack4_act<0>(v); s += (v.x * v.x + v.y * v.y) + (v.z * v.z + v.w * v.w); }
.LBB0_102:
	s_or_b64 exec, exec, s[20:21]
	v_cvt_pk_bf16_f32 v22, v224, v225
	v_cvt_pk_bf16_f32 v23, v226, v227
	s_and_saveexec_b64 s[20:21], s[10:11]
	s_xor_b64 s[20:21], exec, s[20:21]
	s_cbranch_execz .LBB0_104
	v_add_u32_e32 v24, 0x4000, v72
	v_mov_b32_e32 v25, v73
	v_lshl_add_u64 v[24:25], v[24:25], 4, v[36:37]
	global_store_dwordx2 v[24:25], v[22:23], off

; __device__ __forceinline__ size_t sfrag(int r, int k) { return ((size_t)(((k >> 5) * 8 + (r >> 4)) * 64 + ((k >> 3) & 3) * 16 + (r & 15))) * 8 + (k & 7); }
; __device__ __forceinline__ void prologue_phase(CArgs* a, LAS unsigned char* lds, int wg, int G) {
;     ...
; #pragma unroll
;         for (int j = 0; j < 8; ++j) { const f32x4 v = xr[64 * j]; if (m < MP) bo[64 * j] = pack4_act<0>(v); else *(unsigned long long*)(XB + (size_t)MP * D + sfrag(m - MP, 4 * (lane + 64 * j))) = pack4_act<0>(v); s += (v.x * v.x + v.y * v.y) + (v.z * v.z + v.w * v.w); }
.LBB0_106:
	s_or_b64 exec, exec, s[20:21]
	v_cvt_pk_bf16_f32 v26, v228, v229
	v_cvt_pk_bf16_f32 v27, v230, v231
	s_and_saveexec_b64 s[20:21], s[10:11]
	s_xor_b64 s[20:21], exec, s[20:21]
	s_cbranch_execz .LBB0_108
	v_add_u32_e32 v28, 0x5000, v72
	v_mov_b32_e32 v29, v73
	v_lshl_add_u64 v[28:29], v[28:29], 4, v[36:37]
	global_store_dwordx2 v[28:29], v[26:27], off

; __device__ __forceinline__ size_t sfrag(int r, int k) { return ((size_t)(((k >> 5) * 8 + (r >> 4)) * 64 + ((k >> 3) & 3) * 16 + (r & 15))) * 8 + (k & 7); }
; __device__ __forceinline__ void prologue_phase(CArgs* a, LAS unsigned char* lds, int wg, int G) {
;     ...
; #pragma unroll
;         for (int j = 0; j < 8; ++j) { const f32x4 v = xr[64 * j]; if (m < MP) bo[64 * j] = pack4_act<0>(v); else *(unsigned long long*)(XB + (size_t)MP * D + sfrag(m - MP, 4 * (lane + 64 * j))) = pack4_act<0>(v); s += (v.x * v.x + v.y * v.y) + (v.z * v.z + v.w * v.w); }
.LBB0_110:
	s_or_b64 exec, exec, s[20:21]
	v_cvt_pk_bf16_f32 v32, v232, v233
	v_cvt_pk_bf16_f32 v33, v234, v235
	s_and_saveexec_b64 s[20:21], s[10:11]
	s_xor_b64 s[20:21], exec, s[20:21]
	s_cbranch_execz .LBB0_112
	v_add_u32_e32 v50, 0x6000, v72
	v_mov_b32_e32 v51, v73
	v_lshl_add_u64 v[50:51], v[50:51], 4, v[36:37]
	global_store_dwordx2 v[50:51], v[32:33], off

; __device__ __forceinline__ size_t sfrag(int r, int k) { return ((size_t)(((k >> 5) * 8 + (r >> 4)) * 64 + ((k >> 3) & 3) * 16 + (r & 15))) * 8 + (k & 7); }
; __device__ __forceinline__ void prologue_phase(CArgs* a, LAS unsigned char* lds, int wg, int G) {
;     ...
;         const float* src = m < MP ? a->in[0] + (size_t)m * D : a->in[1] + (size_t)(m - MP) * D;
;         const f32x4* xr = (const f32x4*)src + lane; unsigned long long* bo = (unsigned long long*)(XB + (size_t)m * D) + lane;
;         float s = 0.f;
; #pragma unroll
;         for (int j = 0; j < 8; ++j) { const f32x4 v = xr[64 * j]; if (m < MP) bo[64 * j] = pack4_act<0>(v); else *(unsigned long long*)(XB + (size_t)MP * D + sfrag(m - MP, 4 * (lane + 64 * j))) = pack4_act<0>(v); s += (v.x * v.x + v.y * v.y) + (v.z * v.z + v.w * v.w); }
.LBB0_114:
	s_or_b64 exec, exec, s[20:21]
	v_cvt_pk_bf16_f32 v50, v236, v237
	v_cvt_pk_bf16_f32 v51, v238, v239
	s_and_saveexec_b64 s[20:21], s[10:11]
	s_xor_b64 s[10:11], exec, s[20:21]
	s_cbranch_execz .LBB0_116
	v_add_u32_e32 v72, 0x7000, v72
	v_lshl_add_u64 v[48:49], v[72:73], 4, v[36:37]
	global_store_dwordx2 v[48:49], v[50:51], off

; __device__ __forceinline__ size_t sfrag(int r, int k) { return ((size_t)(((k >> 5) * 8 + (r >> 4)) * 64 + ((k >> 3) & 3) * 16 + (r & 15))) * 8 + (k & 7); }
; __device__ __forceinline__ float wave_sum(float v) {
; #pragma unroll
;     for (int o = 1; o < 64; o <<= 1) v += __shfl_xor(v, o);
;     return v;
; }
; __device__ __forceinline__ void prologue_phase(CArgs* a, LAS unsigned char* lds, int wg, int G) {
;     ...
;         for (int j = 0; j < 8; ++j) { const f32x4 v = xr[64 * j]; if (m < MP) bo[64 * j] = pack4_act<0>(v); else *(unsigned long long*)(XB + (size_t)MP * D + sfrag(m - MP, 4 * (lane + 64 * j))) = pack4_act<0>(v); s += (v.x * v.x + v.y * v.y) + (v.z * v.z + v.w * v.w); }
;         s = wave_sum(s);
;         if (lane < 32) ssq[(size_t)m * 32 + lane] = lane == 0 ? s : 0.f;
;     }
.LBB0_118:
	s_or_b64 exec, exec, s[10:11]
	v_mul_f32_e32 v3, v3, v3
	v_fmac_f32_e32 v3, v2, v2
	v_mul_f32_e32 v2, v5, v5
	v_fmac_f32_e32 v2, v4, v4
	v_add_f32_e32 v2, v3, v2
	v_mul_f32_e32 v3, v213, v213
	v_mul_f32_e32 v4, v215, v215
	v_fmac_f32_e32 v3, v212, v212
	v_fmac_f32_e32 v4, v214, v214
	v_add_f32_e32 v3, v3, v4
	v_add_f32_e32 v2, v2, v3
	v_mul_f32_e32 v3, v217, v217
	v_mul_f32_e32 v4, v219, v219
	v_fmac_f32_e32 v3, v216, v216
	v_fmac_f32_e32 v4, v218, v218
	v_add_f32_e32 v3, v3, v4
	v_add_f32_e32 v2, v2, v3
	v_mul_f32_e32 v3, v221, v221
	v_mul_f32_e32 v4, v223, v223
	v_fmac_f32_e32 v3, v220, v220
	v_fmac_f32_e32 v4, v222, v222
	v_add_f32_e32 v3, v3, v4
	v_add_f32_e32 v2, v2, v3
	v_mul_f32_e32 v3, v225, v225
	v_mul_f32_e32 v4, v227, v227
	v_fmac_f32_e32 v3, v224, v224
	v_fmac_f32_e32 v4, v226, v226
	v_add_f32_e32 v3, v3, v4
	v_add_f32_e32 v2, v2, v3
	v_mul_f32_e32 v3, v229, v229
	v_mul_f32_e32 v4, v231, v231
	v_fmac_f32_e32 v3, v228, v228
	v_fmac_f32_e32 v4, v230, v230
	v_add_f32_e32 v3, v3, v4
	v_add_f32_e32 v2, v2, v3
	v_mul_f32_e32 v3, v233, v233
	v_mul_f32_e32 v4, v235, v235
	v_fmac_f32_e32 v3, v232, v232
	v_fmac_f32_e32 v4, v234, v234
	v_add_f32_e32 v3, v3, v4
	v_add_f32_e32 v2, v2, v3
	v_mul_f32_e32 v3, v237, v237
	v_mul_f32_e32 v4, v239, v239
	v_fmac_f32_e32 v3, v236, v236
	v_fmac_f32_e32 v4, v238, v238
	v_add_f32_e32 v3, v3, v4
	v_add_f32_e32 v2, v2, v3
	ds_bpermute_b32 v3, v53, v2
	s_waitcnt lgkmcnt(0)
	v_add_f32_e32 v2, v2, v3
	ds_bpermute_b32 v3, v54, v2
	s_waitcnt lgkmcnt(0)
	v_add_f32_e32 v2, v2, v3
	ds_bpermute_b32 v3, v55, v2
	s_waitcnt lgkmcnt(0)
	v_add_f32_e32 v2, v2, v3
	ds_bpermute_b32 v3, v56, v2
	s_waitcnt lgkmcnt(0)
	v_add_f32_e32 v2, v2, v3
	ds_bpermute_b32 v3, v57, v2
	s_waitcnt lgkmcnt(0)
	v_add_f32_e32 v2, v2, v3
	ds_bpermute_b32 v3, v58, v2
	s_and_saveexec_b64 s[10:11], s[6:7]
	s_cbranch_execz .LBB0_81
	s_waitcnt lgkmcnt(0)
	v_add_f32_e32 v2, v2, v3
	v_cndmask_b32_e64 v4, 0, v2, s[8:9]
	v_lshlrev_b64 v[2:3], 7, v[46:47]
	v_lshl_add_u64 v[2:3], v[38:39], 0, v[2:3]
	global_store_dword v[2:3], v4, off
	s_branch .LBB0_81

; __device__ __forceinline__ float bf_lo(unsigned w) { return __uint_as_float(w << 16); }
; __device__ __forceinline__ float bf_hi(unsigned w) { return __uint_as_float(w & 0xffff0000u); }
; __device__ __forceinline__ size_t sfrag(int r, int k) { return ((size_t)(((k >> 5) * 8 + (r >> 4)) * 64 + ((k >> 3) & 3) * 16 + (r & 15))) * 8 + (k & 7); }
; __device__ __forceinline__ void final_norm_phase(CArgs* a, int wg, int G) {
;     ...
;     for (int m = gw; m < MT; m += NGW) {
;         const u32x2* xr = (const u32x2*)(XB + (size_t)m * D) + lane; f32x4* yo = (f32x4*)(a->out + (m < MP ? O_YP + (size_t)m * D : O_YS + (size_t)(m - MP) * D)) + lane;
;         f32x4 v[8]; float s = 0.f;
; #pragma unroll
;         for (int j = 0; j < 8; ++j) { const u32x2 w = m < MP ? xr[64 * j] : *(const u32x2*)(XB + (size_t)MP * D + sfrag(m - MP, 4 * (lane + 64 * j))); v[j] = (f32x4){bf_lo(w.x), bf_hi(w.x), bf_lo(w.y), bf_hi(w.y)}; s += (v[j].x * v[j].x + v[j].y * v[j].y) + (v[j].z * v[j].z + v[j].w * v[j].w); }
;         const float rs = __builtin_amdgcn_rsqf(wave_sum(s) * (1.0f / D) + EPS);
.LBB0_2131:
	v_add_u32_e32 v2, 0xffffe000, v22
	v_lshlrev_b64 v[60:61], 11, v[2:3]
	v_lshrrev_b32_e32 v2, 4, v2
	v_and_or_b32 v38, v22, 15, v24
	v_add_u32_e32 v2, v2, v23
	v_lshl_or_b32 v2, v2, 6, v38
	v_lshl_add_u64 v[20:21], v[18:19], 0, s[6:7]
	v_cmp_gt_i32_e32 vcc, s22, v22
	v_lshl_add_u64 v[62:63], v[2:3], 4, v[0:1]
	v_mov_b32_e32 v39, v3
	v_cndmask_b32_e32 v21, v63, v21, vcc
	v_cndmask_b32_e32 v20, v62, v20, vcc
	global_load_dwordx2 v[20:21], v[20:21], off
	v_add_u32_e32 v38, 0x1000, v2
	v_lshl_add_u64 v[36:37], v[18:19], 0, s[10:11]
	v_mov_b32_e32 v43, v3
	v_mov_b32_e32 v47, v3
	v_mov_b32_e32 v51, v3
	v_mov_b32_e32 v55, v3
	v_mov_b32_e32 v59, v3
	v_add_u32_e32 v42, 0x2000, v2
	v_add_u32_e32 v46, 0x3000, v2
	v_add_u32_e32 v50, 0x4000, v2
	v_add_u32_e32 v54, 0x5000, v2
	v_add_u32_e32 v58, 0x6000, v2
	v_add_u32_e32 v2, 0x7000, v2
	v_lshl_add_u64 v[38:39], v[38:39], 4, v[0:1]
	v_lshl_add_u64 v[40:41], v[18:19], 0, s[12:13]
	v_lshl_add_u64 v[44:45], v[18:19], 0, s[14:15]
	v_lshl_add_u64 v[48:49], v[18:19], 0, s[16:17]
	v_lshl_add_u64 v[52:53], v[18:19], 0, s[18:19]
	v_lshl_add_u64 v[56:57], v[18:19], 0, s[20:21]
	v_lshl_add_u64 v[42:43], v[42:43], 4, v[0:1]
	v_lshl_add_u64 v[46:47], v[46:47], 4, v[0:1]
	v_lshl_add_u64 v[50:51], v[50:51], 4, v[0:1]
	v_lshl_add_u64 v[54:55], v[54:55], 4, v[0:1]
	v_lshl_add_u64 v[58:59], v[58:59], 4, v[0:1]
	v_lshl_add_u64 v[62:63], v[2:3], 4, v[0:1]
	v_cndmask_b32_e32 v37, v39, v37, vcc
	v_cndmask_b32_e32 v36, v38, v36, vcc
	global_load_dwordx4 v[32:35], v[4:5], off
	v_cndmask_b32_e32 v39, v43, v41, vcc
	v_cndmask_b32_e32 v38, v42, v40, vcc
	v_cndmask_b32_e32 v41, v47, v45, vcc
	v_cndmask_b32_e32 v40, v46, v44, vcc
	v_cndmask_b32_e32 v43, v51, v49, vcc
	v_cndmask_b32_e32 v42, v50, v48, vcc
	v_cndmask_b32_e32 v45, v55, v53, vcc
	v_cndmask_b32_e32 v44, v54, v52, vcc
	v_cndmask_b32_e32 v47, v59, v57, vcc
	v_cndmask_b32_e32 v46, v58, v56, vcc
	v_cndmask_b32_e32 v49, v63, v19, vcc
	v_cndmask_b32_e32 v48, v62, v18, vcc
	global_load_dwordx2 v[50:51], v[36:37], off
	global_load_dwordx2 v[52:53], v[38:39], off
	global_load_dwordx2 v[54:55], v[40:41], off
	global_load_dwordx2 v[56:57], v[42:43], off
	global_load_dwordx2 v[58:59], v[44:45], off
	global_load_dwordx2 v[62:63], v[46:47], off
	global_load_dwordx2 v[64:65], v[48:49], off
	global_load_dwordx4 v[212:215], v[4:5], off offset:1024
	global_load_dwordx4 v[216:219], v[4:5], off offset:2048
	global_load_dwordx4 v[220:223], v[4:5], off offset:3072
	global_load_dwordx4 v[224:227], v[8:9], off
	global_load_dwordx4 v[228:231], v[10:11], off
	global_load_dwordx4 v[232:235], v[12:13], off
	global_load_dwordx4 v[236:239], v[14:15], off
	v_lshl_add_u64 v[60:61], v[60:61], 0, s[8:9]
	v_cndmask_b32_e32 v61, v61, v17, vcc
	v_cndmask_b32_e32 v60, v60, v16, vcc
	v_lshl_add_u64 v[60:61], v[60:61], 2, v[6:7]
	v_add_u32_e32 v22, s44, v22
	v_lshl_add_u64 v[16:17], v[16:17], 0, s[0:1]
	v_lshl_add_u64 v[18:19], v[18:19], 0, s[2:3]
	s_waitcnt vmcnt(15)
	v_lshlrev_b32_e32 v36, 16, v20
	v_and_b32_e32 v37, 0xffff0000, v20
	v_lshlrev_b32_e32 v20, 16, v21
	v_and_b32_e32 v21, 0xffff0000, v21
	v_mul_f32_e32 v2, v21, v21
	v_mul_f32_e32 v46, v37, v37
	v_pk_fma_f32 v[72:73], v[20:21], v[20:21], v[2:3] op_sel_hi:[1,1,0]
	s_waitcnt vmcnt(13)
	v_and_b32_e32 v41, 0xffff0000, v51
	v_and_b32_e32 v40, 0xffff0000, v50
	s_waitcnt vmcnt(11)
	v_lshlrev_b32_e32 v47, 16, v54
	v_lshlrev_b32_e32 v39, 16, v51
	v_lshlrev_b32_e32 v38, 16, v50
	v_and_b32_e32 v43, 0xffff0000, v52
	v_and_b32_e32 v45, 0xffff0000, v53
	v_pk_mul_f32 v[74:75], v[40:41], v[40:41]
	v_pk_fma_f32 v[76:77], v[36:37], v[36:37], v[46:47] op_sel_hi:[1,1,0]
	v_lshlrev_b32_e32 v42, 16, v52
	v_lshlrev_b32_e32 v44, 16, v53
	v_and_b32_e32 v49, 0xffff0000, v54
	v_lshlrev_b32_e32 v50, 16, v55
	v_and_b32_e32 v51, 0xffff0000, v55
	v_mov_b32_e32 v79, v47
	v_mul_f32_e32 v2, v43, v43
	v_mul_f32_e32 v48, v45, v45
	v_pk_fma_f32 v[74:75], v[38:39], v[38:39], v[74:75]
	v_mov_b32_e32 v46, v76
	v_mov_b32_e32 v78, v72
	v_mul_f32_e32 v84, v49, v49
	v_mul_f32_e32 v92, v50, v50
	v_mul_f32_e32 v93, v51, v51
	v_pk_add_f32 v[72:73], v[76:77], v[72:73]
	v_pk_fma_f32 v[76:77], v[42:43], v[42:43], v[2:3] op_sel_hi:[1,1,0]
	v_pk_fma_f32 v[86:87], v[44:45], v[44:45], v[48:49] op_sel_hi:[1,1,0]
	v_pk_mul_f32 v[78:79], v[46:47], v[78:79]
	v_pk_add_f32 v[74:75], v[74:75], v[74:75] op_sel:[0,1] op_sel_hi:[1,0]
	s_waitcnt vmcnt(10)
	v_and_b32_e32 v55, 0xffff0000, v57
	v_and_b32_e32 v54, 0xffff0000, v56
	v_mov_b32_e32 v77, v92
	v_mov_b32_e32 v87, v93
	v_mov_b32_e32 v73, v79
	v_mov_b32_e32 v75, v84
	v_lshlrev_b32_e32 v53, 16, v57
	v_lshlrev_b32_e32 v52, 16, v56
	v_pk_mul_f32 v[80:81], v[54:55], v[54:55]
	v_pk_add_f32 v[76:77], v[76:77], v[86:87]
	v_pk_add_f32 v[72:73], v[72:73], v[74:75]
	s_waitcnt vmcnt(9)
; __device__ __forceinline__ float bf_lo(unsigned w) { return __uint_as_float(w << 16); }
; __device__ __forceinline__ float bf_hi(unsigned w) { return __uint_as_float(w & 0xffff0000u); }
; __device__ __forceinline__ size_t sfrag(int r, int k) { return ((size_t)(((k >> 5) * 8 + (r >> 4)) * 64 + ((k >> 3) & 3) * 16 + (r & 15))) * 8 + (k & 7); }
; __device__ __forceinline__ void final_norm_phase(CArgs* a, int wg, int G) {
;     ...
;         for (int j = 0; j < 8; ++j) { const u32x2 w = m < MP ? xr[64 * j] : *(const u32x2*)(XB + (size_t)MP * D + sfrag(m - MP, 4 * (lane + 64 * j))); v[j] = (f32x4){bf_lo(w.x), bf_hi(w.x), bf_lo(w.y), bf_hi(w.y)}; s += (v[j].x * v[j].x + v[j].y * v[j].y) + (v[j].z * v[j].z + v[j].w * v[j].w); }
;         const float rs = __builtin_amdgcn_rsqf(wave_sum(s) * (1.0f / D) + EPS);
; #pragma unroll
;         for (int j = 0; j < 8; ++j) yo[64 * j] = v[j] * rs * wv[64 * j];
;     }
	v_lshlrev_b32_e32 v57, 16, v59
	v_lshlrev_b32_e32 v56, 16, v58
	v_and_b32_e32 v59, 0xffff0000, v59
	v_and_b32_e32 v58, 0xffff0000, v58
	s_waitcnt vmcnt(8)
	v_and_b32_e32 v67, 0xffff0000, v62
	v_pk_fma_f32 v[80:81], v[52:53], v[52:53], v[80:81]
	v_pk_add_f32 v[72:73], v[72:73], v[76:77]
	v_lshlrev_b32_e32 v66, 16, v62
	v_lshlrev_b32_e32 v62, 16, v63
	v_and_b32_e32 v63, 0xffff0000, v63
	s_waitcnt vmcnt(7)
	v_lshlrev_b32_e32 v69, 16, v64
	v_pk_mul_f32 v[82:83], v[58:59], v[58:59]
	v_mul_f32_e32 v68, v67, v67
	v_pk_add_f32 v[80:81], v[80:81], v[80:81] op_sel:[0,1] op_sel_hi:[1,0]
	v_pk_add_f32 v[72:73], v[72:73], v[72:73] op_sel:[0,1] op_sel_hi:[1,0]
	v_and_b32_e32 v71, 0xffff0000, v64
	v_lshlrev_b32_e32 v64, 16, v65
	v_and_b32_e32 v65, 0xffff0000, v65
	v_mov_b32_e32 v85, v69
	v_mul_f32_e32 v70, v63, v63
	v_pk_fma_f32 v[82:83], v[56:57], v[56:57], v[82:83]
	v_pk_fma_f32 v[88:89], v[66:67], v[66:67], v[68:69] op_sel_hi:[1,1,0]
	v_mov_b32_e32 v84, v80
	v_mov_b32_e32 v68, v72
	v_mul_f32_e32 v94, v71, v71
	v_mul_f32_e32 v95, v64, v64
	v_mul_f32_e32 v96, v65, v65
	v_pk_fma_f32 v[90:91], v[62:63], v[62:63], v[70:71] op_sel_hi:[1,1,0]
	v_pk_add_f32 v[82:83], v[82:83], v[82:83] op_sel:[0,1] op_sel_hi:[1,0]
	v_pk_add_f32 v[72:73], v[72:73], v[80:81]
	v_pk_mul_f32 v[74:75], v[68:69], v[84:85]
	v_mov_b32_e32 v89, v95
	v_mov_b32_e32 v91, v96
	v_mov_b32_e32 v83, v94
	v_mov_b32_e32 v73, v75
	v_pk_add_f32 v[78:79], v[88:89], v[90:91]
	v_pk_add_f32 v[72:73], v[72:73], v[82:83]
	v_mov_b32_e32 v48, v47
	v_pk_add_f32 v[72:73], v[72:73], v[78:79]
	v_mov_b32_e32 v70, v69
	v_add_f32_e32 v2, v72, v73
	ds_bpermute_b32 v46, v25, v2
	s_waitcnt lgkmcnt(0)
	v_add_f32_e32 v2, v2, v46
	ds_bpermute_b32 v46, v26, v2
	s_waitcnt lgkmcnt(0)
	v_add_f32_e32 v2, v2, v46
	ds_bpermute_b32 v46, v27, v2
	s_waitcnt lgkmcnt(0)
	v_add_f32_e32 v2, v2, v46
	ds_bpermute_b32 v46, v28, v2
	s_waitcnt lgkmcnt(0)
	v_add_f32_e32 v2, v2, v46
	ds_bpermute_b32 v46, v29, v2
	s_waitcnt lgkmcnt(0)
	v_add_f32_e32 v2, v2, v46
	ds_bpermute_b32 v46, v30, v2
	s_waitcnt lgkmcnt(0)
	v_add_f32_e32 v2, v2, v46
	v_fmamk_f32 v2, v2, 0x3a000000, v31
	v_rsq_f32_e32 v2, v2
	s_nop 0
	v_pk_mul_f32 v[36:37], v[2:3], v[36:37] op_sel_hi:[0,1]
	v_pk_mul_f32 v[20:21], v[2:3], v[20:21] op_sel_hi:[0,1]
	v_pk_mul_f32 v[34:35], v[34:35], v[20:21]
	v_pk_mul_f32 v[32:33], v[32:33], v[36:37]
	s_waitcnt vmcnt(0)
	global_store_dwordx4 v[60:61], v[32:35], off
	v_mov_b32_e32 v20, v39
	v_mov_b32_e32 v21, v41
	v_mov_b32_e32 v39, v40
	v_pk_mul_f32 v[20:21], v[2:3], v[20:21] op_sel_hi:[0,1]
	v_pk_mul_f32 v[36:37], v[2:3], v[38:39] op_sel_hi:[0,1]
	v_pk_mul_f32 v[32:33], v[212:213], v[36:37]
	v_pk_mul_f32 v[34:35], v[214:215], v[20:21]
	global_store_dwordx4 v[60:61], v[32:35], off offset:1024
	v_pk_mul_f32 v[20:21], v[2:3], v[44:45] op_sel_hi:[0,1]
	v_pk_mul_f32 v[36:37], v[2:3], v[42:43] op_sel_hi:[0,1]
	v_pk_mul_f32 v[32:33], v[216:217], v[36:37]
	v_pk_mul_f32 v[34:35], v[218:219], v[20:21]
	global_store_dwordx4 v[60:61], v[32:35], off offset:2048
	v_pk_mul_f32 v[20:21], v[50:51], v[2:3] op_sel_hi:[1,0]
	v_pk_mul_f32 v[36:37], v[48:49], v[2:3] op_sel_hi:[1,0]
	v_pk_mul_f32 v[34:35], v[222:223], v[20:21]
	v_pk_mul_f32 v[32:33], v[220:221], v[36:37]
	global_store_dwordx4 v[60:61], v[32:35], off offset:3072
	v_mov_b32_e32 v36, v53
	v_mov_b32_e32 v37, v55
	v_mov_b32_e32 v53, v54
	v_add_co_u32_e32 v20, vcc, s23, v60
	v_pk_mul_f32 v[36:37], v[2:3], v[36:37] op_sel_hi:[0,1]
	v_pk_mul_f32 v[38:39], v[2:3], v[52:53] op_sel_hi:[0,1]
	v_addc_co_u32_e32 v21, vcc, 0, v61, vcc
	v_cmp_lt_i32_e32 vcc, s24, v22
	s_or_b64 s[4:5], vcc, s[4:5]
	v_pk_mul_f32 v[32:33], v[224:225], v[38:39]
	v_pk_mul_f32 v[34:35], v[226:227], v[36:37]
	global_store_dwordx4 v[20:21], v[32:35], off
	v_mov_b32_e32 v36, v57
	v_mov_b32_e32 v37, v59
	v_mov_b32_e32 v57, v58
	v_pk_mul_f32 v[36:37], v[2:3], v[36:37] op_sel_hi:[0,1]
	v_pk_mul_f32 v[38:39], v[2:3], v[56:57] op_sel_hi:[0,1]
	v_pk_mul_f32 v[32:33], v[228:229], v[38:39]
	v_pk_mul_f32 v[34:35], v[230:231], v[36:37]
	global_store_dwordx4 v[20:21], v[32:35], off offset:1024
	v_pk_mul_f32 v[36:37], v[2:3], v[62:63] op_sel_hi:[0,1]
	v_pk_mul_f32 v[38:39], v[2:3], v[66:67] op_sel_hi:[0,1]
	v_pk_mul_f32 v[32:33], v[38:39], v[232:233]
	v_pk_mul_f32 v[34:35], v[36:37], v[234:235]
	global_store_dwordx4 v[20:21], v[32:35], off offset:2048
	v_pk_mul_f32 v[36:37], v[64:65], v[2:3] op_sel_hi:[1,0]
	v_pk_mul_f32 v[38:39], v[70:71], v[2:3] op_sel_hi:[1,0]
	v_pk_mul_f32 v[34:35], v[36:37], v[238:239]
	v_pk_mul_f32 v[32:33], v[38:39], v[236:237]
	global_store_dwordx4 v[20:21], v[32:35], off offset:3072
	s_andn2_b64 exec, exec, s[4:5]
	s_cbranch_execnz .LBB0_2131
